# P4b k-loop: global loads two k-tiles ahead (second staging set in AGPRs) and LDS stores of the next tile interleaved into the MFMA stream, on top of the XCD-local tile order
# baseline (speedup 1.0000x reference)
; __device__ __forceinline__ void phase4b(const Params& p, char* smem) {
;     ...
;   for (int it = blockIdx.x; it < 132 * 8; it += gridDim.x) {
;     const int nt = it & 7, mt = it >> 3;
;     const int m0 = mt * 128, n0 = nt * 128;
;     f32x16 acc[2][2]; zero_acc(acc);
;     LoadBf16 al{MRG + (size_t)m0 * 1024, 1024};
;     gemm_mainloop(acc, al, (const u16*)(ws + OFF_WT_OUT) + (size_t)n0 * 1024, 1024, 1024, smem);
.LBB0_1291:
	s_lshr_b32 s45, s44, 3
	s_and_b32 s45, s45, 7
	s_and_b32 s6, s44, 7
	s_lshl_b32 s6, s6, 3
	s_or_b32 s45, s45, s6
	s_and_b32 s6, s44, 0xffffffc0
	s_or_b32 s45, s45, s6
	s_cmpk_lt_i32 s44, 0x400
	s_cselect_b32 s45, s45, s44
	s_lshl_b32 s6, s45, 4
	s_and_b32 s6, s6, 0xffffff80
	s_ashr_i32 s7, s6, 31
	s_lshl_b64 s[8:9], s[6:7], 11
	s_lshl_b32 s6, s45, 4
	s_and_b32 s6, s6, 0xffffff80
	s_lshl_b32 s7, s45, 7
	s_lshl_b32 s0, s45, 18
	s_and_b32 s45, s7, 0x380
	s_ashr_i32 s7, s6, 31
	s_and_b32 s0, s0, 0x1c0000
	s_lshl_b64 s[10:11], s[6:7], 11
	s_add_u32 s10, s33, s10
	s_addc_u32 s11, s54, s11
	s_lshl_b32 s7, s45, 11
	s_add_u32 s46, s12, s7
	s_addc_u32 s47, s13, 0
	v_lshl_add_u64 v[0:1], s[10:11], 0, v[74:75]
	v_lshl_add_u64 v[8:9], v[0:1], 0, v[76:77]
	v_lshl_add_u64 v[0:1], s[46:47], 0, v[74:75]
	v_lshl_add_u64 v[4:5], v[0:1], 0, v[76:77]
	v_lshl_add_u64 v[0:1], s[10:11], 0, v[78:79]
	v_lshl_add_u64 v[16:17], v[0:1], 0, v[76:77]
	v_lshl_add_u64 v[0:1], s[46:47], 0, v[78:79]
	v_lshl_add_u64 v[12:13], v[0:1], 0, v[76:77]
	v_lshl_add_u64 v[0:1], s[10:11], 0, v[80:81]
	v_lshl_add_u64 v[24:25], v[0:1], 0, v[76:77]
	v_lshl_add_u64 v[0:1], s[46:47], 0, v[80:81]
	v_lshl_add_u64 v[20:21], v[0:1], 0, v[76:77]
	v_lshl_add_u64 v[0:1], s[10:11], 0, v[82:83]
	v_lshl_add_u64 v[32:33], v[0:1], 0, v[76:77]
	v_lshl_add_u64 v[0:1], s[46:47], 0, v[82:83]
	v_lshl_add_u64 v[28:29], v[0:1], 0, v[76:77]
	v_lshl_add_u64 v[0:1], s[10:11], 0, v[84:85]
	v_lshl_add_u64 v[40:41], v[0:1], 0, v[76:77]
	v_lshl_add_u64 v[0:1], s[46:47], 0, v[84:85]
	v_lshl_add_u64 v[36:37], v[0:1], 0, v[76:77]
	v_lshl_add_u64 v[0:1], s[10:11], 0, v[86:87]
	v_lshl_add_u64 v[48:49], v[0:1], 0, v[76:77]
	v_lshl_add_u64 v[0:1], s[46:47], 0, v[86:87]
	v_lshl_add_u64 v[44:45], v[0:1], 0, v[76:77]
	v_lshl_add_u64 v[0:1], s[10:11], 0, v[88:89]
	v_lshl_add_u64 v[56:57], v[0:1], 0, v[76:77]
	v_lshl_add_u64 v[0:1], s[46:47], 0, v[88:89]
	v_lshl_add_u64 v[52:53], v[0:1], 0, v[76:77]
	v_lshl_add_u64 v[0:1], s[10:11], 0, v[90:91]
	v_lshl_add_u64 v[0:1], v[0:1], 0, v[76:77]
	s_barrier
; #define GM_LOAD(kt_) { GM_LOAD1(kt_, 0) GM_LOAD1(kt_, 1) GM_LOAD1(kt_, 2) GM_LOAD1(kt_, 3) GM_LOAD1(kt_, 4) GM_LOAD1(kt_, 5) GM_LOAD1(kt_, 6) GM_LOAD1(kt_, 7) }
; template <class AL>
; __device__ __forceinline__ void gemm_mainloop(f32x16 (&acc)[2][2], const AL& al, const u16* __restrict__ Bt, int ldb, int K, char* smem) {
;     ...
;   __syncthreads();
;   GM_LOAD(0)
;   GM_STORE(0, 0)
;   __syncthreads();
; #pragma unroll 1
;   for (int kt = 0; kt < KT; kt += 2) {
;     if (kt + 1 < KT) { GM_LOAD(kt + 1) }
	global_load_dwordx4 v[0:3], v[0:1], off
	s_nop 0
	global_load_dwordx4 v[4:7], v[4:5], off
	s_nop 0
	global_load_dwordx4 v[8:11], v[8:9], off
	s_nop 0
	global_load_dwordx4 v[12:15], v[12:13], off
	s_nop 0
	global_load_dwordx4 v[16:19], v[16:17], off
	s_nop 0
	global_load_dwordx4 v[20:23], v[20:21], off
	s_nop 0
	global_load_dwordx4 v[24:27], v[24:25], off
	s_nop 0
	global_load_dwordx4 v[28:31], v[28:29], off
	s_nop 0
	global_load_dwordx4 v[32:35], v[32:33], off
	s_nop 0
	global_load_dwordx4 v[36:39], v[36:37], off
	s_nop 0
	global_load_dwordx4 v[40:43], v[40:41], off
	s_nop 0
	global_load_dwordx4 v[44:47], v[44:45], off
	s_nop 0
	global_load_dwordx4 v[48:51], v[48:49], off
	s_nop 0
	global_load_dwordx4 v[52:55], v[52:53], off
	s_nop 0
	global_load_dwordx4 v[56:59], v[56:57], off
	v_lshl_add_u64 v[60:61], s[46:47], 0, v[90:91]
	v_lshl_add_u64 v[60:61], v[60:61], 0, v[76:77]
	global_load_dwordx4 v[60:63], v[60:61], off
	s_mov_b32 s7, 0
	v_accvgpr_write_b32 a0, 0
	v_accvgpr_mov_b32 a1, a123
	v_lshl_add_u64 v[92:93], v[72:73], 0, s[0:1]
	v_lshl_add_u64 v[94:95], v[72:73], 0, s[8:9]
	v_accvgpr_mov_b32 a2, a122
	v_accvgpr_mov_b32 a3, a121
	v_accvgpr_mov_b32 a4, a120
	v_accvgpr_mov_b32 a5, a119
	v_accvgpr_mov_b32 a6, a118
	v_accvgpr_mov_b32 a7, a117
	v_accvgpr_mov_b32 a8, a116
	v_accvgpr_mov_b32 a9, a115
	v_accvgpr_mov_b32 a10, a114
	v_accvgpr_mov_b32 a11, a113
	v_accvgpr_mov_b32 a12, a112
	v_accvgpr_mov_b32 a13, a111
	v_accvgpr_mov_b32 a14, a110
	v_accvgpr_mov_b32 a15, a109
	v_accvgpr_write_b32 a16, 0
	v_accvgpr_mov_b32 a17, a108
	v_accvgpr_mov_b32 a18, a107
	v_accvgpr_mov_b32 a19, a106
	v_accvgpr_mov_b32 a20, a105
	v_accvgpr_mov_b32 a21, a104
	v_accvgpr_mov_b32 a22, a103
	v_accvgpr_mov_b32 a23, a102
	v_accvgpr_mov_b32 a24, a101
	v_accvgpr_mov_b32 a25, a100
	v_accvgpr_mov_b32 a26, a99
	v_accvgpr_mov_b32 a27, a98
	v_accvgpr_mov_b32 a28, a97
	v_accvgpr_mov_b32 a29, a96
	v_accvgpr_mov_b32 a30, a95
	v_accvgpr_mov_b32 a31, a94
	v_accvgpr_write_b32 a32, 0
	v_accvgpr_mov_b32 a33, a93
	v_accvgpr_mov_b32 a34, a92
	v_accvgpr_mov_b32 a35, a91
	v_accvgpr_mov_b32 a36, a90
	v_accvgpr_mov_b32 a37, a89
	v_accvgpr_mov_b32 a38, a88
	v_accvgpr_mov_b32 a39, a87
	v_accvgpr_mov_b32 a40, a86
	v_accvgpr_mov_b32 a41, a85
	v_accvgpr_mov_b32 a42, a84
	v_accvgpr_mov_b32 a43, a83
	v_accvgpr_mov_b32 a44, a82
	v_accvgpr_mov_b32 a45, a81
	v_accvgpr_mov_b32 a46, a80
	v_accvgpr_mov_b32 a47, a79
	v_accvgpr_write_b32 a48, 0
	v_accvgpr_mov_b32 a49, a78
	v_accvgpr_mov_b32 a50, a77
	v_accvgpr_mov_b32 a51, a76
	v_accvgpr_mov_b32 a52, a75
	v_accvgpr_mov_b32 a53, a74
	v_accvgpr_mov_b32 a54, a73
	v_accvgpr_mov_b32 a55, a72
	v_accvgpr_mov_b32 a56, a71
	v_accvgpr_mov_b32 a57, a70
	v_accvgpr_mov_b32 a58, a69
	v_accvgpr_mov_b32 a59, a68
	v_accvgpr_mov_b32 a60, a67
	v_accvgpr_mov_b32 a61, a66
	v_accvgpr_mov_b32 a62, a65
	v_accvgpr_mov_b32 a63, a64
	s_waitcnt vmcnt(15)
	ds_write_b128 v96, v[0:3] offset:30464
	s_waitcnt vmcnt(13)
	ds_write_b128 v96, v[8:11]
	ds_write_b128 v97, v[4:7]
	s_waitcnt vmcnt(11)
	ds_write_b128 v96, v[16:19] offset:4352
	ds_write_b128 v98, v[12:15]
	s_waitcnt vmcnt(9)
	ds_write_b128 v96, v[24:27] offset:8704
	ds_write_b128 v99, v[20:23]
	s_waitcnt vmcnt(7)
	ds_write_b128 v96, v[32:35] offset:13056
	ds_write_b128 v100, v[28:31]
	s_waitcnt vmcnt(5)
	ds_write_b128 v96, v[40:43] offset:17408
	ds_write_b128 v101, v[36:39]
	s_waitcnt vmcnt(3)
	ds_write_b128 v96, v[48:51] offset:21760
	ds_write_b128 v102, v[44:47]
	s_waitcnt vmcnt(1)
	ds_write_b128 v96, v[56:59] offset:26112
	ds_write_b128 v103, v[52:55]
	s_waitcnt vmcnt(0)
	ds_write_b128 v104, v[60:63]
	v_lshl_add_u64 v[2:3], v[94:95], 0, v[70:71]
	v_lshl_add_u64 v[0:1], v[92:93], 0, v[70:71]
	v_add_co_u32_e32 v150, vcc, s20, v2
	s_nop 1
	v_addc_co_u32_e32 v151, vcc, 0, v3, vcc
	global_load_dwordx4 a[192:195], v[150:151], off offset:256
	v_add_co_u32_e32 v152, vcc, s21, v0
	s_nop 1
	v_addc_co_u32_e32 v153, vcc, 0, v1, vcc
	global_load_dwordx4 a[196:199], v[152:153], off offset:256
	v_add_co_u32_e32 v150, vcc, s22, v2
	s_nop 1
	v_addc_co_u32_e32 v151, vcc, 0, v3, vcc
	global_load_dwordx4 a[200:203], v[150:151], off offset:256
	v_add_co_u32_e32 v152, vcc, s23, v0
	s_nop 1
	v_addc_co_u32_e32 v153, vcc, 0, v1, vcc
	global_load_dwordx4 a[204:207], v[152:153], off offset:256
	v_add_co_u32_e32 v150, vcc, s24, v2
	s_nop 1
	v_addc_co_u32_e32 v151, vcc, 0, v3, vcc
	global_load_dwordx4 a[208:211], v[150:151], off offset:256
	v_add_co_u32_e32 v152, vcc, s25, v0
	s_nop 1
	v_addc_co_u32_e32 v153, vcc, 0, v1, vcc
	global_load_dwordx4 a[212:215], v[152:153], off offset:256
	v_add_co_u32_e32 v150, vcc, s26, v2
	s_nop 1
	v_addc_co_u32_e32 v151, vcc, 0, v3, vcc
	global_load_dwordx4 a[216:219], v[150:151], off offset:256
	v_add_co_u32_e32 v152, vcc, s27, v0
	s_nop 1
	v_addc_co_u32_e32 v153, vcc, 0, v1, vcc
	global_load_dwordx4 a[220:223], v[152:153], off offset:256
	v_add_co_u32_e32 v150, vcc, s28, v2
	s_nop 1
	v_addc_co_u32_e32 v151, vcc, 0, v3, vcc
	global_load_dwordx4 a[224:227], v[150:151], off offset:256
	v_add_co_u32_e32 v152, vcc, s29, v0
	s_nop 1
	v_addc_co_u32_e32 v153, vcc, 0, v1, vcc
	global_load_dwordx4 a[228:231], v[152:153], off offset:256
	v_add_co_u32_e32 v150, vcc, s34, v2
	s_nop 1
	v_addc_co_u32_e32 v151, vcc, 0, v3, vcc
	global_load_dwordx4 a[232:235], v[150:151], off offset:256
	v_add_co_u32_e32 v152, vcc, s35, v0
	s_nop 1
	v_addc_co_u32_e32 v153, vcc, 0, v1, vcc
	global_load_dwordx4 a[236:239], v[152:153], off offset:256
	v_add_co_u32_e32 v150, vcc, s36, v2
	s_nop 1
	v_addc_co_u32_e32 v151, vcc, 0, v3, vcc
	global_load_dwordx4 a[240:243], v[150:151], off offset:256
	v_add_co_u32_e32 v152, vcc, s37, v0
	s_nop 1
	v_addc_co_u32_e32 v153, vcc, 0, v1, vcc
	global_load_dwordx4 a[244:247], v[152:153], off offset:256
	v_add_co_u32_e32 v150, vcc, s38, v2
	s_nop 1
	v_addc_co_u32_e32 v151, vcc, 0, v3, vcc
	global_load_dwordx4 a[248:251], v[150:151], off offset:256
	v_add_co_u32_e32 v152, vcc, s39, v0
	s_nop 1
	v_addc_co_u32_e32 v153, vcc, 0, v1, vcc
	global_load_dwordx4 a[252:255], v[152:153], off offset:256
	s_waitcnt lgkmcnt(0)
	s_barrier
	s_branch .LBB0_1293

; #define GM_LOAD(kt_) { GM_LOAD1(kt_, 0) GM_LOAD1(kt_, 1) GM_LOAD1(kt_, 2) GM_LOAD1(kt_, 3) GM_LOAD1(kt_, 4) GM_LOAD1(kt_, 5) GM_LOAD1(kt_, 6) GM_LOAD1(kt_, 7) }
; template <class AL>
; __device__ __forceinline__ void gemm_mainloop(f32x16 (&acc)[2][2], const AL& al, const u16* __restrict__ Bt, int ldb, int K, char* smem) {
;     ...
;   for (int kt = 0; kt < KT; kt += 2) {
;     if (kt + 1 < KT) { GM_LOAD(kt + 1) }
;     GM_COMPUTE(0)
;     if (kt + 1 < KT) { GM_STORE(kt + 1, 1) }
;     __syncthreads();
;     if (kt + 1 < KT) {
;       if (kt + 2 < KT) { GM_LOAD(kt + 2) }
;       GM_COMPUTE(1)
;       if (kt + 2 < KT) { GM_STORE(kt + 2, 0) }
.LBB0_1293:
	v_lshl_add_u64 v[2:3], v[94:95], 0, v[70:71]
	v_lshl_add_u64 v[0:1], v[92:93], 0, v[70:71]
	v_add_co_u32_e32 v150, vcc, s20, v2
	s_nop 1
	v_addc_co_u32_e32 v151, vcc, 0, v3, vcc
	global_load_dwordx4 v[4:7], v[150:151], off offset:512
	v_add_co_u32_e32 v152, vcc, s21, v0
	s_nop 1
	v_addc_co_u32_e32 v153, vcc, 0, v1, vcc
	global_load_dwordx4 v[8:11], v[152:153], off offset:512
	v_add_co_u32_e32 v150, vcc, s22, v2
	s_nop 1
	v_addc_co_u32_e32 v151, vcc, 0, v3, vcc
	global_load_dwordx4 v[12:15], v[150:151], off offset:512
	v_add_co_u32_e32 v152, vcc, s23, v0
	s_nop 1
	v_addc_co_u32_e32 v153, vcc, 0, v1, vcc
	global_load_dwordx4 v[16:19], v[152:153], off offset:512
	v_add_co_u32_e32 v150, vcc, s24, v2
	s_nop 1
	v_addc_co_u32_e32 v151, vcc, 0, v3, vcc
	global_load_dwordx4 v[20:23], v[150:151], off offset:512
	v_add_co_u32_e32 v152, vcc, s25, v0
	s_nop 1
	v_addc_co_u32_e32 v153, vcc, 0, v1, vcc
	global_load_dwordx4 v[24:27], v[152:153], off offset:512
	v_add_co_u32_e32 v150, vcc, s26, v2
	s_nop 1
	v_addc_co_u32_e32 v151, vcc, 0, v3, vcc
	global_load_dwordx4 v[28:31], v[150:151], off offset:512
	v_add_co_u32_e32 v152, vcc, s27, v0
	s_nop 1
	v_addc_co_u32_e32 v153, vcc, 0, v1, vcc
	global_load_dwordx4 v[32:35], v[152:153], off offset:512
	v_add_co_u32_e32 v150, vcc, s28, v2
	s_nop 1
	v_addc_co_u32_e32 v151, vcc, 0, v3, vcc
	global_load_dwordx4 v[36:39], v[150:151], off offset:512
	v_add_co_u32_e32 v152, vcc, s29, v0
	s_nop 1
	v_addc_co_u32_e32 v153, vcc, 0, v1, vcc
	global_load_dwordx4 v[40:43], v[152:153], off offset:512
	v_add_co_u32_e32 v150, vcc, s34, v2
	s_nop 1
	v_addc_co_u32_e32 v151, vcc, 0, v3, vcc
	global_load_dwordx4 v[44:47], v[150:151], off offset:512
	v_add_co_u32_e32 v152, vcc, s35, v0
	s_nop 1
	v_addc_co_u32_e32 v153, vcc, 0, v1, vcc
	global_load_dwordx4 v[48:51], v[152:153], off offset:512
	v_add_co_u32_e32 v150, vcc, s36, v2
	s_nop 1
	v_addc_co_u32_e32 v151, vcc, 0, v3, vcc
	global_load_dwordx4 v[52:55], v[150:151], off offset:512
	v_add_co_u32_e32 v152, vcc, s37, v0
	s_nop 1
	v_addc_co_u32_e32 v153, vcc, 0, v1, vcc
	global_load_dwordx4 v[56:59], v[152:153], off offset:512
	v_add_co_u32_e32 v150, vcc, s38, v2
	s_nop 1
	v_addc_co_u32_e32 v151, vcc, 0, v3, vcc
	global_load_dwordx4 v[60:63], v[150:151], off offset:512
	v_add_co_u32_e32 v152, vcc, s39, v0
	s_nop 1
	v_addc_co_u32_e32 v153, vcc, 0, v1, vcc
	global_load_dwordx4 v[146:149], v[152:153], off offset:512
	ds_read_b128 v[150:153], v106
	ds_read_b128 v[154:157], v106 offset:8704
	ds_read_b128 v[158:161], v108
	ds_read_b128 v[162:165], v109
	ds_read_b128 v[166:169], v110 offset:32
	ds_read_b128 v[170:173], v110 offset:8736
	ds_read_b128 v[174:177], v111 offset:32
	ds_read_b128 v[178:181], v112 offset:32
	s_waitcnt lgkmcnt(5)
	v_mfma_f32_32x32x16_bf16 a[48:63], v[150:153], v[158:161], a[48:63]
	s_waitcnt lgkmcnt(4)
	v_mfma_f32_32x32x16_bf16 a[32:47], v[150:153], v[162:165], a[32:47]
	v_add_u32_e32 v64, 0x19800, v96
	s_waitcnt vmcnt(31)
	ds_write_b128 v96, a[192:195] offset:34816
	v_mfma_f32_32x32x16_bf16 a[16:31], v[154:157], v[158:161], a[16:31]
	v_mfma_f32_32x32x16_bf16 a[0:15], v[154:157], v[162:165], a[0:15]
	s_waitcnt vmcnt(30)
	ds_write_b128 v64, a[196:199]
	ds_read_b128 v[150:153], v112 offset:64
	ds_read_b128 v[154:157], v111 offset:64
	ds_read_b128 v[158:161], v110 offset:8768
	ds_read_b128 v[162:165], v110 offset:64
	s_waitcnt lgkmcnt(5)
	v_mfma_f32_32x32x16_bf16 a[48:63], v[166:169], v[174:177], a[48:63]
	s_waitcnt lgkmcnt(4)
	v_mfma_f32_32x32x16_bf16 a[32:47], v[166:169], v[178:181], a[32:47]
	s_waitcnt vmcnt(29)
	ds_write_b128 v96, a[200:203] offset:39168
	v_mfma_f32_32x32x16_bf16 a[16:31], v[170:173], v[174:177], a[16:31]
	v_mfma_f32_32x32x16_bf16 a[0:15], v[170:173], v[178:181], a[0:15]
	v_add_u32_e32 v64, 0x1a900, v96
	s_waitcnt vmcnt(28)
	ds_write_b128 v64, a[204:207]
	ds_read_b128 v[166:169], v110 offset:96
	ds_read_b128 v[170:173], v110 offset:8800
	ds_read_b128 v[174:177], v111 offset:96
	ds_read_b128 v[178:181], v112 offset:96
	s_waitcnt lgkmcnt(4)
	v_mfma_f32_32x32x16_bf16 a[48:63], v[162:165], v[154:157], a[48:63]
	v_mfma_f32_32x32x16_bf16 a[32:47], v[162:165], v[150:153], a[32:47]
	s_waitcnt vmcnt(27)
	ds_write_b128 v96, a[208:211] offset:43520
	v_mfma_f32_32x32x16_bf16 a[16:31], v[158:161], v[154:157], a[16:31]
	v_mfma_f32_32x32x16_bf16 a[0:15], v[158:161], v[150:153], a[0:15]
	v_add_u32_e32 v64, 0x1ba00, v96
	s_waitcnt vmcnt(26)
	ds_write_b128 v64, a[212:215]
	ds_read_b128 v[150:153], v112 offset:128
	ds_read_b128 v[154:157], v111 offset:128
	ds_read_b128 v[158:161], v110 offset:8832
	ds_read_b128 v[162:165], v110 offset:128
	s_waitcnt lgkmcnt(5)
	v_mfma_f32_32x32x16_bf16 a[48:63], v[166:169], v[174:177], a[48:63]
	s_waitcnt lgkmcnt(4)
	v_mfma_f32_32x32x16_bf16 a[32:47], v[166:169], v[178:181], a[32:47]
	s_waitcnt vmcnt(25)
	ds_write_b128 v96, a[216:219] offset:47872
	v_mfma_f32_32x32x16_bf16 a[16:31], v[170:173], v[174:177], a[16:31]
	v_mfma_f32_32x32x16_bf16 a[0:15], v[170:173], v[178:181], a[0:15]
	v_add_u32_e32 v64, 0x1cb00, v96
	s_waitcnt vmcnt(24)
	ds_write_b128 v64, a[220:223]
	ds_read_b128 v[166:169], v110 offset:160
	ds_read_b128 v[170:173], v110 offset:8864
	ds_read_b128 v[174:177], v111 offset:160
	ds_read_b128 v[178:181], v112 offset:160
	s_waitcnt lgkmcnt(4)
	v_mfma_f32_32x32x16_bf16 a[48:63], v[162:165], v[154:157], a[48:63]
	v_mfma_f32_32x32x16_bf16 a[32:47], v[162:165], v[150:153], a[32:47]
	s_waitcnt vmcnt(23)
	ds_write_b128 v96, a[224:227] offset:52224
	v_mfma_f32_32x32x16_bf16 a[16:31], v[158:161], v[154:157], a[16:31]
	v_mfma_f32_32x32x16_bf16 a[0:15], v[158:161], v[150:153], a[0:15]
	v_add_u32_e32 v64, 0x1dc00, v96
	s_cmp_lt_u32 s7, 6
	s_waitcnt vmcnt(22)
; #define GM_LOAD(kt_) { GM_LOAD1(kt_, 0) GM_LOAD1(kt_, 1) GM_LOAD1(kt_, 2) GM_LOAD1(kt_, 3) GM_LOAD1(kt_, 4) GM_LOAD1(kt_, 5) GM_LOAD1(kt_, 6) GM_LOAD1(kt_, 7) }
; template <class AL>
; __device__ __forceinline__ void gemm_mainloop(f32x16 (&acc)[2][2], const AL& al, const u16* __restrict__ Bt, int ldb, int K, char* smem) {
;     ...
;     GM_COMPUTE(0)
;     if (kt + 1 < KT) { GM_STORE(kt + 1, 1) }
;     __syncthreads();
;     if (kt + 1 < KT) {
;       if (kt + 2 < KT) { GM_LOAD(kt + 2) }
	ds_write_b128 v64, a[228:231]
	ds_read_b128 v[150:153], v112 offset:192
	ds_read_b128 v[154:157], v111 offset:192
	ds_read_b128 v[158:161], v110 offset:8896
	ds_read_b128 v[162:165], v110 offset:192
	s_waitcnt lgkmcnt(5)
	v_mfma_f32_32x32x16_bf16 a[48:63], v[166:169], v[174:177], a[48:63]
	s_waitcnt lgkmcnt(4)
	v_mfma_f32_32x32x16_bf16 a[32:47], v[166:169], v[178:181], a[32:47]
	s_waitcnt vmcnt(21)
	ds_write_b128 v96, a[232:235] offset:56576
	v_mfma_f32_32x32x16_bf16 a[16:31], v[170:173], v[174:177], a[16:31]
	v_mfma_f32_32x32x16_bf16 a[0:15], v[170:173], v[178:181], a[0:15]
	v_add_u32_e32 v64, 0x1ed00, v96
	s_cselect_b64 s[10:11], -1, 0
	s_cmp_gt_u32 s7, 5
	s_waitcnt vmcnt(20)
	ds_write_b128 v64, a[236:239]
	ds_read_b128 v[166:169], v110 offset:224
	ds_read_b128 v[170:173], v110 offset:8928
	ds_read_b128 v[174:177], v111 offset:224
	ds_read_b128 v[178:181], v112 offset:224
	s_waitcnt lgkmcnt(4)
	v_mfma_f32_32x32x16_bf16 a[48:63], v[162:165], v[154:157], a[48:63]
	v_mfma_f32_32x32x16_bf16 a[32:47], v[162:165], v[150:153], a[32:47]
	s_waitcnt vmcnt(19)
	ds_write_b128 v96, a[240:243] offset:60928
	v_mfma_f32_32x32x16_bf16 a[16:31], v[158:161], v[154:157], a[16:31]
	v_mfma_f32_32x32x16_bf16 a[0:15], v[158:161], v[150:153], a[0:15]
	s_waitcnt lgkmcnt(1)
	v_mfma_f32_32x32x16_bf16 a[48:63], v[166:169], v[174:177], a[48:63]
	s_waitcnt lgkmcnt(0)
	v_mfma_f32_32x32x16_bf16 a[32:47], v[166:169], v[178:181], a[32:47]
	v_add_u32_e32 v64, 0x1fe00, v96
	s_cselect_b64 s[8:9], -1, 0
	s_waitcnt vmcnt(18)
	ds_write_b128 v64, a[244:247]
	s_waitcnt vmcnt(17)
	ds_write_b128 v96, a[248:251] offset:65280
	v_mfma_f32_32x32x16_bf16 a[16:31], v[170:173], v[174:177], a[16:31]
	v_mfma_f32_32x32x16_bf16 a[0:15], v[170:173], v[178:181], a[0:15]
	v_add_u32_e32 v64, 0x20f00, v96
	s_and_b64 vcc, exec, s[8:9]
	s_waitcnt vmcnt(16)
	ds_write_b128 v64, a[252:255]
	s_waitcnt lgkmcnt(0)
	s_barrier
	s_cbranch_vccnz .LBB0_1295
	v_add_co_u32_e32 v150, vcc, 0x3bb5000, v2
	s_nop 1
	v_addc_co_u32_e32 v151, vcc, 0, v3, vcc
	global_load_dwordx4 a[192:195], v[150:151], off offset:768
	v_add_co_u32_e32 v152, vcc, 0xe00000, v0
	s_nop 1
	v_addc_co_u32_e32 v153, vcc, 0, v1, vcc
	global_load_dwordx4 a[196:199], v[152:153], off offset:768
	v_add_co_u32_e32 v150, vcc, 0x3bbd000, v2
	s_nop 1
	v_addc_co_u32_e32 v151, vcc, 0, v3, vcc
	global_load_dwordx4 a[200:203], v[150:151], off offset:768
	v_add_co_u32_e32 v152, vcc, 0xe08000, v0
	s_nop 1
	v_addc_co_u32_e32 v153, vcc, 0, v1, vcc
	global_load_dwordx4 a[204:207], v[152:153], off offset:768
	v_add_co_u32_e32 v150, vcc, 0x3bc5000, v2
	s_nop 1
	v_addc_co_u32_e32 v151, vcc, 0, v3, vcc
	global_load_dwordx4 a[208:211], v[150:151], off offset:768
	v_add_co_u32_e32 v152, vcc, 0xe10000, v0
	s_nop 1
	v_addc_co_u32_e32 v153, vcc, 0, v1, vcc
	global_load_dwordx4 a[212:215], v[152:153], off offset:768
	v_add_co_u32_e32 v150, vcc, 0x3bcd000, v2
	s_nop 1
	v_addc_co_u32_e32 v151, vcc, 0, v3, vcc
	global_load_dwordx4 a[216:219], v[150:151], off offset:768
	v_add_co_u32_e32 v152, vcc, 0xe18000, v0
	s_nop 1
	v_addc_co_u32_e32 v153, vcc, 0, v1, vcc
	global_load_dwordx4 a[220:223], v[152:153], off offset:768
	v_add_co_u32_e32 v150, vcc, 0x3bd5000, v2
	s_nop 1
	v_addc_co_u32_e32 v151, vcc, 0, v3, vcc
	global_load_dwordx4 a[224:227], v[150:151], off offset:768
	v_add_co_u32_e32 v152, vcc, 0xe20000, v0
	s_nop 1
	v_addc_co_u32_e32 v153, vcc, 0, v1, vcc
	global_load_dwordx4 a[228:231], v[152:153], off offset:768
	v_add_co_u32_e32 v150, vcc, 0x3bdd000, v2
	s_nop 1
	v_addc_co_u32_e32 v151, vcc, 0, v3, vcc
	global_load_dwordx4 a[232:235], v[150:151], off offset:768
	v_add_co_u32_e32 v152, vcc, 0xe28000, v0
	s_nop 1
	v_addc_co_u32_e32 v153, vcc, 0, v1, vcc
	global_load_dwordx4 a[236:239], v[152:153], off offset:768
	v_add_co_u32_e32 v150, vcc, 0x3be5000, v2
	s_nop 1
	v_addc_co_u32_e32 v151, vcc, 0, v3, vcc
	global_load_dwordx4 a[240:243], v[150:151], off offset:768
	v_add_co_u32_e32 v152, vcc, 0xe30000, v0
	s_nop 1
	v_addc_co_u32_e32 v153, vcc, 0, v1, vcc
	global_load_dwordx4 a[244:247], v[152:153], off offset:768
	v_add_co_u32_e32 v150, vcc, 0x3bed000, v2
	s_nop 1
	v_addc_co_u32_e32 v151, vcc, 0, v3, vcc
	global_load_dwordx4 a[248:251], v[150:151], off offset:768
	v_add_co_u32_e32 v152, vcc, 0xe38000, v0
	s_nop 1
	v_addc_co_u32_e32 v153, vcc, 0, v1, vcc
	global_load_dwordx4 a[252:255], v[152:153], off offset:768
; #define GM_LOAD(kt_) { GM_LOAD1(kt_, 0) GM_LOAD1(kt_, 1) GM_LOAD1(kt_, 2) GM_LOAD1(kt_, 3) GM_LOAD1(kt_, 4) GM_LOAD1(kt_, 5) GM_LOAD1(kt_, 6) GM_LOAD1(kt_, 7) }
; template <class AL>
; __device__ __forceinline__ void gemm_mainloop(f32x16 (&acc)[2][2], const AL& al, const u16* __restrict__ Bt, int ldb, int K, char* smem) {
;     ...
;     if (kt + 1 < KT) {
;       if (kt + 2 < KT) { GM_LOAD(kt + 2) }
;       GM_COMPUTE(1)
;       if (kt + 2 < KT) { GM_STORE(kt + 2, 0) }
;       __syncthreads();
.LBB0_1295:
	ds_read_b128 v[0:3], v106 offset:34816
	ds_read_b128 v[150:153], v106 offset:43520
	ds_read_b128 v[154:157], v113
	ds_read_b128 v[158:161], v114
	ds_read_b128 v[162:165], v110 offset:34848
	ds_read_b128 v[166:169], v110 offset:43552
	ds_read_b128 v[170:173], v115 offset:32
	ds_read_b128 v[174:177], v116 offset:32
	s_waitcnt lgkmcnt(5)
	v_mfma_f32_32x32x16_bf16 a[48:63], v[0:3], v[154:157], a[48:63]
	s_waitcnt lgkmcnt(4)
	v_mfma_f32_32x32x16_bf16 a[32:47], v[0:3], v[158:161], a[32:47]
	s_waitcnt vmcnt(31)
	ds_write_b128 v96, v[4:7]
	v_mfma_f32_32x32x16_bf16 a[16:31], v[150:153], v[154:157], a[16:31]
	v_mfma_f32_32x32x16_bf16 a[0:15], v[150:153], v[158:161], a[0:15]
	s_waitcnt vmcnt(30)
	ds_write_b128 v97, v[8:11]
	ds_read_b128 v[0:3], v116 offset:64
	ds_read_b128 v[150:153], v115 offset:64
	ds_read_b128 v[154:157], v110 offset:43584
	ds_read_b128 v[158:161], v110 offset:34880
	s_waitcnt lgkmcnt(5)
	v_mfma_f32_32x32x16_bf16 a[48:63], v[162:165], v[170:173], a[48:63]
	s_waitcnt lgkmcnt(4)
	v_mfma_f32_32x32x16_bf16 a[32:47], v[162:165], v[174:177], a[32:47]
	s_waitcnt vmcnt(29)
	ds_write_b128 v96, v[12:15] offset:4352
	v_mfma_f32_32x32x16_bf16 a[16:31], v[166:169], v[170:173], a[16:31]
	v_mfma_f32_32x32x16_bf16 a[0:15], v[166:169], v[174:177], a[0:15]
	s_waitcnt vmcnt(28)
	ds_write_b128 v98, v[16:19]
	ds_read_b128 v[162:165], v110 offset:34912
	ds_read_b128 v[166:169], v110 offset:43616
	ds_read_b128 v[170:173], v115 offset:96
	ds_read_b128 v[174:177], v116 offset:96
	s_waitcnt lgkmcnt(4)
	v_mfma_f32_32x32x16_bf16 a[48:63], v[158:161], v[150:153], a[48:63]
	v_mfma_f32_32x32x16_bf16 a[32:47], v[158:161], v[0:3], a[32:47]
	s_waitcnt vmcnt(27)
	ds_write_b128 v96, v[20:23] offset:8704
	v_mfma_f32_32x32x16_bf16 a[16:31], v[154:157], v[150:153], a[16:31]
	v_mfma_f32_32x32x16_bf16 a[0:15], v[154:157], v[0:3], a[0:15]
	s_waitcnt vmcnt(26)
	ds_write_b128 v99, v[24:27]
	ds_read_b128 v[0:3], v116 offset:128
	ds_read_b128 v[150:153], v115 offset:128
	ds_read_b128 v[154:157], v110 offset:43648
	ds_read_b128 v[158:161], v110 offset:34944
	s_waitcnt lgkmcnt(5)
	v_mfma_f32_32x32x16_bf16 a[48:63], v[162:165], v[170:173], a[48:63]
	s_waitcnt lgkmcnt(4)
	v_mfma_f32_32x32x16_bf16 a[32:47], v[162:165], v[174:177], a[32:47]
	s_waitcnt vmcnt(25)
	ds_write_b128 v96, v[28:31] offset:13056
	v_mfma_f32_32x32x16_bf16 a[16:31], v[166:169], v[170:173], a[16:31]
	v_mfma_f32_32x32x16_bf16 a[0:15], v[166:169], v[174:177], a[0:15]
	s_waitcnt vmcnt(24)
	ds_write_b128 v100, v[32:35]
	ds_read_b128 v[162:165], v110 offset:34976
	ds_read_b128 v[166:169], v110 offset:43680
	ds_read_b128 v[170:173], v115 offset:160
	ds_read_b128 v[174:177], v116 offset:160
	s_waitcnt lgkmcnt(4)
	v_mfma_f32_32x32x16_bf16 a[48:63], v[158:161], v[150:153], a[48:63]
	v_mfma_f32_32x32x16_bf16 a[32:47], v[158:161], v[0:3], a[32:47]
	s_waitcnt vmcnt(23)
	ds_write_b128 v96, v[36:39] offset:17408
	v_mfma_f32_32x32x16_bf16 a[16:31], v[154:157], v[150:153], a[16:31]
	v_mfma_f32_32x32x16_bf16 a[0:15], v[154:157], v[0:3], a[0:15]
	s_waitcnt vmcnt(22)
	ds_write_b128 v101, v[40:43]
	ds_read_b128 v[0:3], v116 offset:192
	ds_read_b128 v[150:153], v115 offset:192
	ds_read_b128 v[154:157], v110 offset:43712
	ds_read_b128 v[158:161], v110 offset:35008
	s_waitcnt lgkmcnt(5)
	v_mfma_f32_32x32x16_bf16 a[48:63], v[162:165], v[170:173], a[48:63]
	s_waitcnt lgkmcnt(4)
	v_mfma_f32_32x32x16_bf16 a[32:47], v[162:165], v[174:177], a[32:47]
	s_waitcnt vmcnt(21)
	ds_write_b128 v96, v[44:47] offset:21760
	v_mfma_f32_32x32x16_bf16 a[16:31], v[166:169], v[170:173], a[16:31]
	v_mfma_f32_32x32x16_bf16 a[0:15], v[166:169], v[174:177], a[0:15]
	s_waitcnt vmcnt(20)
	ds_write_b128 v102, v[48:51]
	ds_read_b128 v[162:165], v110 offset:35040
	ds_read_b128 v[166:169], v110 offset:43744
	ds_read_b128 v[170:173], v115 offset:224
	ds_read_b128 v[174:177], v116 offset:224
	s_waitcnt lgkmcnt(4)
	v_mfma_f32_32x32x16_bf16 a[48:63], v[158:161], v[150:153], a[48:63]
	v_mfma_f32_32x32x16_bf16 a[32:47], v[158:161], v[0:3], a[32:47]
	s_waitcnt vmcnt(19)
	ds_write_b128 v96, v[52:55] offset:26112
	v_mfma_f32_32x32x16_bf16 a[16:31], v[154:157], v[150:153], a[16:31]
	v_mfma_f32_32x32x16_bf16 a[0:15], v[154:157], v[0:3], a[0:15]
	s_waitcnt lgkmcnt(1)
	v_mfma_f32_32x32x16_bf16 a[48:63], v[162:165], v[170:173], a[48:63]
	s_waitcnt lgkmcnt(0)
	v_mfma_f32_32x32x16_bf16 a[32:47], v[162:165], v[174:177], a[32:47]
	s_waitcnt vmcnt(18)
	ds_write_b128 v103, v[56:59]
	s_waitcnt vmcnt(17)
	ds_write_b128 v96, v[60:63] offset:30464
	v_mfma_f32_32x32x16_bf16 a[16:31], v[166:169], v[170:173], a[16:31]
	v_mfma_f32_32x32x16_bf16 a[0:15], v[166:169], v[174:177], a[0:15]
	s_waitcnt vmcnt(16)
	ds_write_b128 v104, v[146:149]
	s_branch .LBB0_1292
; __device__ __forceinline__ int rowmap(int e, int lane) { return (e & 3) + 8 * (e >> 2) + 4 * (lane >> 5); }
; __device__ __forceinline__ void phase4b(const Params& p, char* smem) {
;     ...
; #pragma unroll
;     for (int i = 0; i < 2; i++)
; #pragma unroll
;       for (int e = 0; e < 16; e++) {
;         const int row = m0 + wm * 64 + i * 32 + rowmap(e, lane);
;         const float* xr = xrow(p, row);
;         float sq = 0.f;
; #pragma unroll
;         for (int j = 0; j < 2; j++) {
;           const int col = n0 + wn * 64 + j * 32 + (lane & 31);
;           float v = acc[i][j][e] + xr[col];
.LBB0_1297:
	s_waitcnt vmcnt(0)
	s_nop 7
	v_accvgpr_read_b32 v48, a48
	v_accvgpr_read_b32 v49, a49
	v_accvgpr_read_b32 v50, a50
	v_accvgpr_read_b32 v51, a51
	v_accvgpr_read_b32 v52, a52
	v_accvgpr_read_b32 v53, a53
	v_accvgpr_read_b32 v54, a54
	v_accvgpr_read_b32 v55, a55
	v_accvgpr_read_b32 v56, a56
	v_accvgpr_read_b32 v57, a57
	v_accvgpr_read_b32 v58, a58
	v_accvgpr_read_b32 v59, a59
	v_accvgpr_read_b32 v60, a60
	v_accvgpr_read_b32 v61, a61
	v_accvgpr_read_b32 v62, a62
	v_accvgpr_read_b32 v63, a63
	v_accvgpr_read_b32 v32, a32
	v_accvgpr_read_b32 v33, a33
	v_accvgpr_read_b32 v34, a34
	v_accvgpr_read_b32 v35, a35
	v_accvgpr_read_b32 v36, a36
	v_accvgpr_read_b32 v37, a37
	v_accvgpr_read_b32 v38, a38
	v_accvgpr_read_b32 v39, a39
	v_accvgpr_read_b32 v40, a40
	v_accvgpr_read_b32 v41, a41
	v_accvgpr_read_b32 v42, a42
	v_accvgpr_read_b32 v43, a43
	v_accvgpr_read_b32 v44, a44
	v_accvgpr_read_b32 v45, a45
	v_accvgpr_read_b32 v46, a46
	v_accvgpr_read_b32 v47, a47
	v_accvgpr_read_b32 v16, a16
	v_accvgpr_read_b32 v17, a17
	v_accvgpr_read_b32 v18, a18
	v_accvgpr_read_b32 v19, a19
	v_accvgpr_read_b32 v20, a20
	v_accvgpr_read_b32 v21, a21
	v_accvgpr_read_b32 v22, a22
	v_accvgpr_read_b32 v23, a23
	v_accvgpr_read_b32 v24, a24
	v_accvgpr_read_b32 v25, a25
	v_accvgpr_read_b32 v26, a26
	v_accvgpr_read_b32 v27, a27
	v_accvgpr_read_b32 v28, a28
	v_accvgpr_read_b32 v29, a29
	v_accvgpr_read_b32 v30, a30
	v_accvgpr_read_b32 v31, a31
	v_accvgpr_read_b32 v0, a0
	v_accvgpr_read_b32 v1, a1
	v_accvgpr_read_b32 v2, a2
	v_accvgpr_read_b32 v3, a3
	v_accvgpr_read_b32 v4, a4
	v_accvgpr_read_b32 v5, a5
	v_accvgpr_read_b32 v6, a6
	v_accvgpr_read_b32 v7, a7
	v_accvgpr_read_b32 v8, a8
	v_accvgpr_read_b32 v9, a9
	v_accvgpr_read_b32 v10, a10
	v_accvgpr_read_b32 v11, a11
	v_accvgpr_read_b32 v12, a12
	v_accvgpr_read_b32 v13, a13
	v_accvgpr_read_b32 v14, a14
	v_accvgpr_read_b32 v15, a15
	v_add_u32_e32 v135, s6, v105
	v_or_b32_e32 v94, v135, v117
	v_cmp_le_i32_e32 vcc, s14, v94
	v_mov_b32_e32 v64, s42
	v_mov_b32_e32 v137, s40
	v_mov_b32_e32 v95, 0
	v_cndmask_b32_e32 v146, v137, v64, vcc
	v_mov_b32_e32 v64, s43
	v_mov_b32_e32 v137, s41
	v_or_b32_e32 v148, 32, v135
	v_cndmask_b32_e32 v147, v137, v64, vcc
	v_mov_b32_e32 v64, 0xfc000000
	v_cndmask_b32_e32 v92, 0, v64, vcc
	v_cndmask_b32_e64 v93, 0, -1, vcc
	v_lshl_add_u64 v[146:147], v[92:93], 0, v[146:147]
	v_or_b32_e32 v64, s45, v107
	v_lshlrev_b32_e32 v64, 2, v64
	v_lshl_add_u64 v[146:147], v[64:65], 0, v[146:147]
	v_add_lshl_u32 v94, v135, v117, 12
	v_lshl_add_u64 v[92:93], v[94:95], 0, v[146:147]
	global_load_dword a48, v[92:93], off
	global_load_dword a32, v[92:93], off offset:128
	v_add_lshl_u32 v94, v135, v120, 12
	v_lshl_add_u64 v[92:93], v[94:95], 0, v[146:147]
	global_load_dword a49, v[92:93], off
	global_load_dword a33, v[92:93], off offset:128
	v_add_lshl_u32 v94, v135, v121, 12
	v_lshl_add_u64 v[92:93], v[94:95], 0, v[146:147]
	global_load_dword a50, v[92:93], off
	global_load_dword a34, v[92:93], off offset:128
	v_add_lshl_u32 v94, v135, v122, 12
	v_lshl_add_u64 v[92:93], v[94:95], 0, v[146:147]
	global_load_dword a51, v[92:93], off
	global_load_dword a35, v[92:93], off offset:128
	v_add_lshl_u32 v94, v135, v123, 12
	v_lshl_add_u64 v[92:93], v[94:95], 0, v[146:147]
	global_load_dword a52, v[92:93], off
	global_load_dword a36, v[92:93], off offset:128
	v_add_lshl_u32 v94, v135, v124, 12
	v_lshl_add_u64 v[92:93], v[94:95], 0, v[146:147]
	global_load_dword a53, v[92:93], off
	global_load_dword a37, v[92:93], off offset:128
	v_add_lshl_u32 v94, v135, v125, 12
	v_lshl_add_u64 v[92:93], v[94:95], 0, v[146:147]
	global_load_dword a54, v[92:93], off
	global_load_dword a38, v[92:93], off offset:128
	v_add_lshl_u32 v94, v135, v126, 12
	v_lshl_add_u64 v[92:93], v[94:95], 0, v[146:147]
	global_load_dword a55, v[92:93], off
	global_load_dword a39, v[92:93], off offset:128
	v_add_lshl_u32 v94, v135, v127, 12
	v_lshl_add_u64 v[92:93], v[94:95], 0, v[146:147]
	global_load_dword a56, v[92:93], off
	global_load_dword a40, v[92:93], off offset:128
	v_add_lshl_u32 v94, v135, v128, 12
	v_lshl_add_u64 v[92:93], v[94:95], 0, v[146:147]
	global_load_dword a57, v[92:93], off
	global_load_dword a41, v[92:93], off offset:128
	v_add_lshl_u32 v94, v135, v129, 12
	v_lshl_add_u64 v[92:93], v[94:95], 0, v[146:147]
	global_load_dword a58, v[92:93], off
	global_load_dword a42, v[92:93], off offset:128
	v_add_lshl_u32 v94, v135, v130, 12
	v_lshl_add_u64 v[92:93], v[94:95], 0, v[146:147]
	global_load_dword a59, v[92:93], off
	global_load_dword a43, v[92:93], off offset:128
	v_add_lshl_u32 v94, v135, v131, 12
	v_lshl_add_u64 v[92:93], v[94:95], 0, v[146:147]
	global_load_dword a60, v[92:93], off
	global_load_dword a44, v[92:93], off offset:128
	v_add_lshl_u32 v94, v135, v132, 12
	v_lshl_add_u64 v[92:93], v[94:95], 0, v[146:147]
	global_load_dword a61, v[92:93], off
	global_load_dword a45, v[92:93], off offset:128
	v_add_lshl_u32 v94, v135, v133, 12
	v_lshl_add_u64 v[92:93], v[94:95], 0, v[146:147]
	global_load_dword a62, v[92:93], off
; __device__ __forceinline__ u16 f2bf(float f) { return (u16)(pack2(f, f) & 0xffffu); }
; __device__ __forceinline__ float sum32(float v) { v = dpp_row_sum16(v); v += __shfl_xor(v, 16); return v; }
; __device__ __forceinline__ int rowmap(int e, int lane) { return (e & 3) + 8 * (e >> 2) + 4 * (lane >> 5); }
; __device__ __forceinline__ void phase4b(const Params& p, char* smem) {
;     ...
;     for (int i = 0; i < 2; i++)
; #pragma unroll
;       for (int e = 0; e < 16; e++) {
;         const int row = m0 + wm * 64 + i * 32 + rowmap(e, lane);
;         const float* xr = xrow(p, row);
;         float sq = 0.f;
; #pragma unroll
;         for (int j = 0; j < 2; j++) {
;           const int col = n0 + wn * 64 + j * 32 + (lane & 31);
;           float v = acc[i][j][e] + xr[col];
;           X1[(size_t)row * 1024 + col] = v;
;           ((u16*)smem)[(row - m0) * 136 + (col - n0)] = f2bf(v);
;           sq += v * v;
;         }
;         sq = sum32(sq);
;         if ((lane & 31) == 0) atomicAdd(&SSQ1[row], sq);
	global_load_dword a46, v[92:93], off offset:128
	v_add_lshl_u32 v94, v135, v134, 12
	v_lshl_add_u64 v[92:93], v[94:95], 0, v[146:147]
	global_load_dword a63, v[92:93], off
	global_load_dword a47, v[92:93], off offset:128
	v_add_lshl_u32 v94, v148, v117, 12
	v_lshl_add_u64 v[92:93], v[94:95], 0, v[146:147]
	global_load_dword a16, v[92:93], off
	global_load_dword a0, v[92:93], off offset:128
	v_add_lshl_u32 v94, v148, v120, 12
	v_lshl_add_u64 v[92:93], v[94:95], 0, v[146:147]
	global_load_dword a17, v[92:93], off
	global_load_dword a1, v[92:93], off offset:128
	v_add_lshl_u32 v94, v148, v121, 12
	v_lshl_add_u64 v[92:93], v[94:95], 0, v[146:147]
	global_load_dword a18, v[92:93], off
	global_load_dword a2, v[92:93], off offset:128
	v_add_lshl_u32 v94, v148, v122, 12
	v_lshl_add_u64 v[92:93], v[94:95], 0, v[146:147]
	global_load_dword a19, v[92:93], off
	global_load_dword a3, v[92:93], off offset:128
	v_add_lshl_u32 v94, v148, v123, 12
	v_lshl_add_u64 v[92:93], v[94:95], 0, v[146:147]
	global_load_dword a20, v[92:93], off
	global_load_dword a4, v[92:93], off offset:128
	v_add_lshl_u32 v94, v148, v124, 12
	v_lshl_add_u64 v[92:93], v[94:95], 0, v[146:147]
	global_load_dword a21, v[92:93], off
	global_load_dword a5, v[92:93], off offset:128
	v_add_lshl_u32 v94, v148, v125, 12
	v_lshl_add_u64 v[92:93], v[94:95], 0, v[146:147]
	global_load_dword a22, v[92:93], off
	global_load_dword a6, v[92:93], off offset:128
	v_add_lshl_u32 v94, v148, v126, 12
	v_lshl_add_u64 v[92:93], v[94:95], 0, v[146:147]
	global_load_dword a23, v[92:93], off
	global_load_dword a7, v[92:93], off offset:128
	v_add_lshl_u32 v94, v148, v127, 12
	v_lshl_add_u64 v[92:93], v[94:95], 0, v[146:147]
	global_load_dword a24, v[92:93], off
	global_load_dword a8, v[92:93], off offset:128
	v_add_lshl_u32 v94, v148, v128, 12
	v_lshl_add_u64 v[92:93], v[94:95], 0, v[146:147]
	global_load_dword a25, v[92:93], off
	global_load_dword a9, v[92:93], off offset:128
	v_add_lshl_u32 v94, v148, v129, 12
	v_lshl_add_u64 v[92:93], v[94:95], 0, v[146:147]
	global_load_dword a26, v[92:93], off
	global_load_dword a10, v[92:93], off offset:128
	v_add_lshl_u32 v94, v148, v130, 12
	v_lshl_add_u64 v[92:93], v[94:95], 0, v[146:147]
	global_load_dword a27, v[92:93], off
	global_load_dword a11, v[92:93], off offset:128
	v_add_lshl_u32 v94, v148, v131, 12
	v_lshl_add_u64 v[92:93], v[94:95], 0, v[146:147]
	global_load_dword a28, v[92:93], off
	global_load_dword a12, v[92:93], off offset:128
	v_add_lshl_u32 v94, v148, v132, 12
	v_lshl_add_u64 v[92:93], v[94:95], 0, v[146:147]
	global_load_dword a29, v[92:93], off
	global_load_dword a13, v[92:93], off offset:128
	v_add_lshl_u32 v94, v148, v133, 12
	v_lshl_add_u64 v[92:93], v[94:95], 0, v[146:147]
	global_load_dword a30, v[92:93], off
	global_load_dword a14, v[92:93], off offset:128
	v_add_lshl_u32 v94, v148, v134, 12
	v_lshl_add_u64 v[92:93], v[94:95], 0, v[146:147]
	global_load_dword a31, v[92:93], off
	global_load_dword a15, v[92:93], off offset:128
	s_waitcnt vmcnt(0)
	v_add_u32_e32 v135, s6, v105
	v_or_b32_e32 v94, v135, v117
	v_add_u32_e32 v64, 0xffffc000, v94
	v_cmp_gt_i32_e32 vcc, s14, v94
	v_ashrrev_i32_e32 v95, 31, v94
	v_mov_b32_e32 v137, s41
	v_cndmask_b32_e32 v92, v64, v94, vcc
	v_mov_b32_e32 v64, s43
	v_cndmask_b32_e32 v93, 0, v95, vcc
	v_cndmask_b32_e32 v147, v64, v137, vcc
	v_mov_b32_e32 v64, s42
	v_mov_b32_e32 v137, s40
	v_cndmask_b32_e32 v146, v64, v137, vcc
	v_lshlrev_b64 v[92:93], 12, v[92:93]
	v_or_b32_e32 v64, s45, v107
	v_lshl_add_u64 v[146:147], v[146:147], 0, v[92:93]
	v_lshlrev_b32_e32 v64, 2, v64
	v_lshl_add_u64 v[92:93], v[146:147], 0, v[64:65]
	v_accvgpr_read_b32 v137, a48
	v_lshlrev_b64 v[148:149], 12, v[94:95]
	v_add_u32_e32 v92, s45, v107
	v_lshl_add_u64 v[148:149], s[78:79], 0, v[148:149]
	v_mov_b32_e32 v93, v65
	v_lshlrev_b32_e32 v92, 2, v92
	v_lshl_add_u64 v[150:151], v[148:149], 0, v[64:65]
	v_lshl_add_u64 v[146:147], v[146:147], 0, v[92:93]
	v_lshl_add_u64 v[148:149], v[148:149], 0, v[92:93]
	v_add_f32_e32 v48, v48, v137
	global_store_dword v[150:151], v48, off
	v_accvgpr_read_b32 v137, a32
	v_cvt_pk_bf16_f32 v150, v48, s0
	v_subrev_u32_e32 v146, s6, v94
	v_mad_u64_u32 v[146:147], s[8:9], v146, s15, v[68:69]
	ds_write_b16 v146, v150
	v_add_f32_e32 v137, v32, v137
	v_mul_f32_e32 v32, v137, v137
	v_fmac_f32_e32 v32, v48, v48
	global_store_dword v[148:149], v137, off offset:128
	v_cvt_pk_bf16_f32 v137, v137, s0
	v_add_f32_dpp v32, v32, v32 quad_perm:[1,0,3,2] row_mask:0xf bank_mask:0xf bound_ctrl:1
	ds_write_b16 v146, v137 offset:64
	s_nop 0
	v_add_f32_dpp v32, v32, v32 quad_perm:[2,3,0,1] row_mask:0xf bank_mask:0xf bound_ctrl:1
	s_nop 1
	v_add_f32_dpp v32, v32, v32 row_half_mirror row_mask:0xf bank_mask:0xf bound_ctrl:1
	s_nop 1
	v_add_f32_dpp v32, v32, v32 row_mirror row_mask:0xf bank_mask:0xf bound_ctrl:1
	ds_bpermute_b32 v48, v118, v32
	s_and_saveexec_b64 s[8:9], s[4:5]
	s_cbranch_execz .LBB0_1299
	s_waitcnt lgkmcnt(0)
	v_add_f32_e32 v32, v32, v48
	v_lshl_add_u64 v[94:95], v[94:95], 2, s[94:95]
	global_atomic_add_f32 v[94:95], v32, off
